# incremental next-unit tile index for all four GEMMs (w_out/down: pn same, pm+=8)
# baseline (speedup 1.0000x reference)
.LBB0_427:
	s_add_i32 s93, s93, 1
	s_mul_i32 s2, s93, s94
	s_mul_hi_u32 s3, s93, s9
	s_add_i32 s3, s3, s2
	s_mul_i32 s2, s93, s9
	s_add_u32 s40, s2, s17
	s_addc_u32 s41, s3, s95
	v_cmp_gt_i64_e32 vcc, s[40:41], v[212:213]
	v_cmp_lt_i64_e64 s[36:37], s[40:41], v[210:211]
	s_cbranch_vccnz .LBB0_433
	s_mov_b32 s56, s28
	s_add_i32 s60, s22, 8

.LBB0_643:
	s_add_i32 s64, s64, 1
	s_mul_i32 s2, s64, s96
	s_mul_hi_u32 s3, s64, s9
	s_add_i32 s3, s3, s2
	s_mul_i32 s2, s64, s9
	s_add_u32 s36, s2, s17
	s_addc_u32 s37, s3, s97
	v_cmp_gt_i64_e32 vcc, s[36:37], v[212:213]
	v_cmp_lt_i64_e64 s[38:39], s[36:37], v[210:211]
	s_cbranch_vccnz .LBB0_649
	s_mov_b32 s33, s80
	s_add_i32 s11, s26, 8
